# FF1 epilogue: redundant canonicalising v_max folded into the relu max (128 fewer VALU per tile), wait states kept after the wide stores
# speedup vs baseline: 1.0082x; 1.0082x over previous
; #define PG8_STAGE(bufoff, gbase, voff) do { _Pragma("unroll") for (int _i = 0; _i < 2; ++_i) \
;         __builtin_amdgcn_global_load_lds((const unsigned*)((const char*)(gbase) + (voff)[_i]), (LAS unsigned*)(lds + (bufoff) + ldsw + _i * 8192), 16, 0, 0); } while (0)
; #define PG8_LDA(dst, b, h) do { _Pragma("unroll") for (int m = 0; m < 4; ++m) _Pragma("unroll") for (int k = 0; k < 2; ++k) dst[m][k] = *(const LAS bf16x8*)(lds + PG8_SA(b, h) + aoff + m * 2048 + k * 1024); } while (0)
; #define PG8_LDB(dst, b, h) do { _Pragma("unroll") for (int n = 0; n < 2; ++n) _Pragma("unroll") for (int k = 0; k < 2; ++k) dst[n][k] = *(const LAS bf16x8*)(lds + PG8_SB(b, h) + boff + n * 2048 + k * 1024); } while (0)
; #define PG8_MMA(ai, bj, At, Bt) do { __builtin_amdgcn_s_setprio(1); _Pragma("unroll") for (int m = 0; m < 4; ++m) _Pragma("unroll") for (int n = 0; n < 2; ++n) _Pragma("unroll") for (int k = 0; k < 2; ++k) \
;         acc[ai][bj][m][n] = __builtin_amdgcn_mfma_f32_16x16x32_bf16(Bt[n][k], At[m][k], acc[ai][bj][m][n], 0, 0, 0); __builtin_amdgcn_s_setprio(0); } while (0)
; #define PG8_WAIT_V(n) asm volatile("s_waitcnt vmcnt(" #n ")" ::: "memory")
; #define PG8_WAIT_L(n) asm volatile("s_waitcnt lgkmcnt(" #n ")" ::: "memory")
; #define PG8_BAR __builtin_amdgcn_s_barrier()
; #define PG8_SCHED __builtin_amdgcn_sched_barrier(0)
; template <class Epi, class Sched>
; __device__ __forceinline__ void gemm_phase(LAS unsigned char* lds, const Gemm g, const Sched& S, const Epi& E) {
;     ...
;             PG8_LDB(B0, 0, 0); PG8_SCHED; PG8_LDA(At, 0, 0); PG8_STAGE(PG8_SA(1, 1), a1 + hstep, voffA);
;             PG8_WAIT_L(8); PG8_BAR; PG8_WAIT_L(0); PG8_MMA(0, 0, At, B0); PG8_BAR; PG8_SCHED;
;             PG8_LDB(B1, 0, 1); PG8_STAGE(PG8_SB(0, 0), b2, voffB);
;             PG8_BAR; PG8_WAIT_L(0); PG8_MMA(0, 1, At, B1); PG8_BAR;
;             PG8_LDA(At, 0, 1); PG8_STAGE(PG8_SA(0, 0), a2, voffA);
;             PG8_BAR; PG8_WAIT_L(0); PG8_MMA(1, 0, At, B0); PG8_BAR; PG8_SCHED;
;             PG8_STAGE(PG8_SB(0, 1), b2 + hstep, voffB);
;             PG8_WAIT_V(6); PG8_BAR; PG8_MMA(1, 1, At, B1); PG8_BAR;
.LBB0_1279:
	s_nop 0
	v_add_u32_e32 v140, s47, v143
	ds_read_b128 v[146:149], v140
	ds_read_b128 v[150:153], v140 offset:1024
	ds_read_b128 v[154:157], v140 offset:2048
	ds_read_b128 v[158:161], v140 offset:3072
	s_add_u32 s22, s20, 0xfff80080
	s_addc_u32 s23, s21, -1
	s_cmp_eq_u32 s43, 28
	s_cselect_b32 s25, s3, s23
	s_cselect_b32 s24, s11, s22
	s_cselect_b32 s23, s9, s42
	s_cselect_b32 s22, s40, s41
	s_add_i32 m0, s17, 0xc000
	ds_read_b128 v[162:165], v145
	ds_read_b128 v[166:169], v145 offset:1024
	ds_read_b128 v[170:173], v145 offset:2048
	ds_read_b128 v[174:177], v145 offset:3072
	ds_read_b128 v[178:181], v145 offset:4096
	ds_read_b128 v[182:185], v145 offset:5120
	ds_read_b128 v[186:189], v145 offset:6144
	ds_read_b128 v[190:193], v145 offset:7168
	global_load_lds_dwordx4 v136, s[20:21]
	s_add_i32 m0, s17, 0xe000
	s_nop 0
	global_load_lds_dwordx4 v138, s[20:21]
	s_waitcnt lgkmcnt(8)
	s_barrier
	s_waitcnt lgkmcnt(0)
	v_mfma_f32_16x16x32_bf16 v[126:129], v[146:149], v[162:165], v[126:129]
	v_mfma_f32_16x16x32_bf16 v[122:125], v[154:157], v[162:165], v[122:125]
	v_mfma_f32_16x16x32_bf16 v[110:113], v[146:149], v[170:173], v[110:113]
	v_mfma_f32_16x16x32_bf16 v[106:109], v[154:157], v[170:173], v[106:109]
	v_mfma_f32_16x16x32_bf16 v[94:97], v[146:149], v[178:181], v[94:97]
	v_mfma_f32_16x16x32_bf16 v[90:93], v[154:157], v[178:181], v[90:93]
	v_mfma_f32_16x16x32_bf16 v[78:81], v[146:149], v[186:189], v[78:81]
	v_mfma_f32_16x16x32_bf16 v[74:77], v[154:157], v[186:189], v[74:77]
	v_mfma_f32_16x16x32_bf16 v[126:129], v[150:153], v[166:169], v[126:129]
	v_mfma_f32_16x16x32_bf16 v[122:125], v[158:161], v[166:169], v[122:125]
	v_mfma_f32_16x16x32_bf16 v[110:113], v[150:153], v[174:177], v[110:113]
	v_mfma_f32_16x16x32_bf16 v[106:109], v[158:161], v[174:177], v[106:109]
	v_mfma_f32_16x16x32_bf16 v[94:97], v[150:153], v[182:185], v[94:97]
	v_mfma_f32_16x16x32_bf16 v[90:93], v[158:161], v[182:185], v[90:93]
	v_mfma_f32_16x16x32_bf16 v[78:81], v[150:153], v[190:193], v[78:81]
	v_mfma_f32_16x16x32_bf16 v[74:77], v[158:161], v[190:193], v[74:77]
	s_barrier
	s_add_i32 s46, 0, 0x14000
	v_add_u32_e32 v140, s46, v143
	s_add_i32 s44, s47, s30
	ds_read_b128 v[194:197], v140
	ds_read_b128 v[198:201], v140 offset:1024
	ds_read_b128 v[202:205], v140 offset:2048
	ds_read_b128 v[206:209], v140 offset:3072
	s_mov_b32 m0, s44
	s_nop 0
	global_load_lds_dwordx4 v0, s[22:23]
	s_add_i32 m0, s44, 0x2000
	s_nop 0
	global_load_lds_dwordx4 v130, s[22:23]
	s_barrier
	s_waitcnt lgkmcnt(0)
	v_mfma_f32_16x16x32_bf16 v[118:121], v[194:197], v[162:165], v[118:121]
	v_mfma_f32_16x16x32_bf16 v[114:117], v[202:205], v[162:165], v[114:117]
	v_mfma_f32_16x16x32_bf16 v[102:105], v[194:197], v[170:173], v[102:105]
	v_mfma_f32_16x16x32_bf16 v[98:101], v[202:205], v[170:173], v[98:101]
	v_mfma_f32_16x16x32_bf16 v[86:89], v[194:197], v[178:181], v[86:89]
	v_mfma_f32_16x16x32_bf16 v[82:85], v[202:205], v[178:181], v[82:85]
	v_mfma_f32_16x16x32_bf16 v[70:73], v[194:197], v[186:189], v[70:73]
	v_mfma_f32_16x16x32_bf16 v[66:69], v[202:205], v[186:189], v[66:69]
	v_mfma_f32_16x16x32_bf16 v[118:121], v[198:201], v[166:169], v[118:121]
	v_mfma_f32_16x16x32_bf16 v[114:117], v[206:209], v[166:169], v[114:117]
	v_mfma_f32_16x16x32_bf16 v[102:105], v[198:201], v[174:177], v[102:105]
	v_mfma_f32_16x16x32_bf16 v[98:101], v[206:209], v[174:177], v[98:101]
	v_mfma_f32_16x16x32_bf16 v[86:89], v[198:201], v[182:185], v[86:89]
	v_mfma_f32_16x16x32_bf16 v[82:85], v[206:209], v[182:185], v[82:85]
	v_mfma_f32_16x16x32_bf16 v[70:73], v[198:201], v[190:193], v[70:73]
	v_mfma_f32_16x16x32_bf16 v[66:69], v[206:209], v[190:193], v[66:69]
	s_mov_b32 m0, s17
	s_add_u32 s48, s24, 0x80
	s_addc_u32 s49, s25, 0
	s_barrier
	ds_read_b128 v[162:165], v145 offset:16384
	ds_read_b128 v[166:169], v145 offset:17408
	ds_read_b128 v[170:173], v145 offset:18432
	ds_read_b128 v[174:177], v145 offset:19456
	ds_read_b128 v[178:181], v145 offset:20480
	ds_read_b128 v[182:185], v145 offset:21504
	ds_read_b128 v[186:189], v145 offset:22528
	ds_read_b128 v[190:193], v145 offset:23552
	global_load_lds_dwordx4 v134, s[24:25]
	s_mov_b32 m0, s19
	s_nop 0
	global_load_lds_dwordx4 v132, s[24:25]
	s_barrier
	s_waitcnt lgkmcnt(0)
	v_mfma_f32_16x16x32_bf16 v[62:65], v[146:149], v[162:165], v[62:65]
	v_mfma_f32_16x16x32_bf16 v[58:61], v[154:157], v[162:165], v[58:61]
	v_mfma_f32_16x16x32_bf16 v[46:49], v[146:149], v[170:173], v[46:49]
	v_mfma_f32_16x16x32_bf16 v[42:45], v[154:157], v[170:173], v[42:45]
	v_mfma_f32_16x16x32_bf16 v[30:33], v[146:149], v[178:181], v[30:33]
	v_mfma_f32_16x16x32_bf16 v[26:29], v[154:157], v[178:181], v[26:29]
	v_mfma_f32_16x16x32_bf16 v[14:17], v[146:149], v[186:189], v[14:17]
	v_mfma_f32_16x16x32_bf16 v[10:13], v[154:157], v[186:189], v[10:13]
	v_mfma_f32_16x16x32_bf16 v[62:65], v[150:153], v[166:169], v[62:65]
	v_mfma_f32_16x16x32_bf16 v[58:61], v[158:161], v[166:169], v[58:61]
	v_mfma_f32_16x16x32_bf16 v[46:49], v[150:153], v[174:177], v[46:49]
	v_mfma_f32_16x16x32_bf16 v[42:45], v[158:161], v[174:177], v[42:45]
	v_mfma_f32_16x16x32_bf16 v[30:33], v[150:153], v[182:185], v[30:33]
	v_mfma_f32_16x16x32_bf16 v[26:29], v[158:161], v[182:185], v[26:29]
	v_mfma_f32_16x16x32_bf16 v[14:17], v[150:153], v[190:193], v[14:17]
	v_mfma_f32_16x16x32_bf16 v[10:13], v[158:161], v[190:193], v[10:13]
	s_barrier
	s_add_u32 s44, s22, 0x80000
	s_addc_u32 s45, s23, 0
	s_add_i32 s46, s46, s30
	s_mov_b32 m0, s46
	s_nop 0
	global_load_lds_dwordx4 v0, s[44:45]
	s_add_i32 m0, s46, 0x2000
	s_nop 0
	global_load_lds_dwordx4 v130, s[44:45]
	s_waitcnt vmcnt(6)
	s_barrier
; #define PG8_STAGE(bufoff, gbase, voff) do { _Pragma("unroll") for (int _i = 0; _i < 2; ++_i) \
;         __builtin_amdgcn_global_load_lds((const unsigned*)((const char*)(gbase) + (voff)[_i]), (LAS unsigned*)(lds + (bufoff) + ldsw + _i * 8192), 16, 0, 0); } while (0)
; #define PG8_LDA(dst, b, h) do { _Pragma("unroll") for (int m = 0; m < 4; ++m) _Pragma("unroll") for (int k = 0; k < 2; ++k) dst[m][k] = *(const LAS bf16x8*)(lds + PG8_SA(b, h) + aoff + m * 2048 + k * 1024); } while (0)
; #define PG8_LDB(dst, b, h) do { _Pragma("unroll") for (int n = 0; n < 2; ++n) _Pragma("unroll") for (int k = 0; k < 2; ++k) dst[n][k] = *(const LAS bf16x8*)(lds + PG8_SB(b, h) + boff + n * 2048 + k * 1024); } while (0)
; #define PG8_MMA(ai, bj, At, Bt) do { __builtin_amdgcn_s_setprio(1); _Pragma("unroll") for (int m = 0; m < 4; ++m) _Pragma("unroll") for (int n = 0; n < 2; ++n) _Pragma("unroll") for (int k = 0; k < 2; ++k) \
;         acc[ai][bj][m][n] = __builtin_amdgcn_mfma_f32_16x16x32_bf16(Bt[n][k], At[m][k], acc[ai][bj][m][n], 0, 0, 0); __builtin_amdgcn_s_setprio(0); } while (0)
; #define PG8_WAIT_V(n) asm volatile("s_waitcnt vmcnt(" #n ")" ::: "memory")
; #define PG8_WAIT_L(n) asm volatile("s_waitcnt lgkmcnt(" #n ")" ::: "memory")
; #define PG8_BAR __builtin_amdgcn_s_barrier()
; #define PG8_SCHED __builtin_amdgcn_sched_barrier(0)
; template <class Epi, class Sched>
; __device__ __forceinline__ void gemm_phase(LAS unsigned char* lds, const Gemm g, const Sched& S, const Epi& E) {
;     ...
;             PG8_WAIT_V(6); PG8_BAR; PG8_MMA(1, 1, At, B1); PG8_BAR;
;             PG8_LDB(B0, 1, 0); PG8_SCHED; PG8_LDA(At, 1, 0); PG8_STAGE(PG8_SA(0, 1), a2 + hstep, voffA);
;             PG8_WAIT_L(8); PG8_BAR; PG8_WAIT_L(0); PG8_MMA(0, 0, At, B0); PG8_BAR; PG8_SCHED;
;             PG8_LDB(B1, 1, 1); PG8_STAGE(PG8_SB(1, 0), b3, voffB);
;             PG8_BAR; PG8_WAIT_L(0); PG8_MMA(0, 1, At, B1); PG8_BAR;
;             PG8_LDA(At, 1, 1); PG8_STAGE(PG8_SA(1, 0), a3, voffA);
	v_mfma_f32_16x16x32_bf16 v[54:57], v[194:197], v[162:165], v[54:57]
	v_mfma_f32_16x16x32_bf16 v[50:53], v[202:205], v[162:165], v[50:53]
	v_mfma_f32_16x16x32_bf16 v[38:41], v[194:197], v[170:173], v[38:41]
	v_mfma_f32_16x16x32_bf16 v[34:37], v[202:205], v[170:173], v[34:37]
	v_mfma_f32_16x16x32_bf16 v[22:25], v[194:197], v[178:181], v[22:25]
	v_mfma_f32_16x16x32_bf16 v[18:21], v[202:205], v[178:181], v[18:21]
	v_mfma_f32_16x16x32_bf16 v[6:9], v[194:197], v[186:189], v[6:9]
	v_mfma_f32_16x16x32_bf16 v[2:5], v[202:205], v[186:189], v[2:5]
	v_mfma_f32_16x16x32_bf16 v[54:57], v[198:201], v[166:169], v[54:57]
	v_mfma_f32_16x16x32_bf16 v[50:53], v[206:209], v[166:169], v[50:53]
	v_mfma_f32_16x16x32_bf16 v[38:41], v[198:201], v[174:177], v[38:41]
	v_mfma_f32_16x16x32_bf16 v[34:37], v[206:209], v[174:177], v[34:37]
	v_mfma_f32_16x16x32_bf16 v[22:25], v[198:201], v[182:185], v[22:25]
	v_mfma_f32_16x16x32_bf16 v[18:21], v[206:209], v[182:185], v[18:21]
	v_mfma_f32_16x16x32_bf16 v[6:9], v[198:201], v[190:193], v[6:9]
	v_mfma_f32_16x16x32_bf16 v[2:5], v[206:209], v[190:193], v[2:5]
	s_add_i32 s44, 0, 0x18000
	v_add_u32_e32 v158, s44, v143
	s_barrier
	ds_read_b128 v[146:149], v158
	ds_read_b128 v[150:153], v158 offset:1024
	ds_read_b128 v[154:157], v158 offset:2048
	ds_read_b128 v[158:161], v158 offset:3072
	s_add_u32 s24, s24, 0x80000
	s_addc_u32 s25, s25, 0
	s_mov_b32 m0, s35
	ds_read_b128 v[162:165], v145 offset:32768
	ds_read_b128 v[166:169], v145 offset:33792
	ds_read_b128 v[170:173], v145 offset:34816
	ds_read_b128 v[174:177], v145 offset:35840
	ds_read_b128 v[178:181], v145 offset:36864
	ds_read_b128 v[182:185], v145 offset:37888
	ds_read_b128 v[186:189], v145 offset:38912
	ds_read_b128 v[190:193], v145 offset:39936
	global_load_lds_dwordx4 v134, s[24:25]
	s_mov_b32 m0, s36
	s_nop 0
	global_load_lds_dwordx4 v132, s[24:25]
	s_waitcnt lgkmcnt(8)
	s_barrier
	s_waitcnt lgkmcnt(0)
	v_mfma_f32_16x16x32_bf16 v[126:129], v[146:149], v[162:165], v[126:129]
	v_mfma_f32_16x16x32_bf16 v[122:125], v[154:157], v[162:165], v[122:125]
	v_mfma_f32_16x16x32_bf16 v[110:113], v[146:149], v[170:173], v[110:113]
	v_mfma_f32_16x16x32_bf16 v[106:109], v[154:157], v[170:173], v[106:109]
	v_mfma_f32_16x16x32_bf16 v[94:97], v[146:149], v[178:181], v[94:97]
	v_mfma_f32_16x16x32_bf16 v[90:93], v[154:157], v[178:181], v[90:93]
	v_mfma_f32_16x16x32_bf16 v[78:81], v[146:149], v[186:189], v[78:81]
	v_mfma_f32_16x16x32_bf16 v[74:77], v[154:157], v[186:189], v[74:77]
	v_mfma_f32_16x16x32_bf16 v[126:129], v[150:153], v[166:169], v[126:129]
	v_mfma_f32_16x16x32_bf16 v[122:125], v[158:161], v[166:169], v[122:125]
	v_mfma_f32_16x16x32_bf16 v[110:113], v[150:153], v[174:177], v[110:113]
	v_mfma_f32_16x16x32_bf16 v[106:109], v[158:161], v[174:177], v[106:109]
	v_mfma_f32_16x16x32_bf16 v[94:97], v[150:153], v[182:185], v[94:97]
	v_mfma_f32_16x16x32_bf16 v[90:93], v[158:161], v[182:185], v[90:93]
	v_mfma_f32_16x16x32_bf16 v[78:81], v[150:153], v[190:193], v[78:81]
	v_mfma_f32_16x16x32_bf16 v[74:77], v[158:161], v[190:193], v[74:77]
	s_barrier
	s_add_i32 s24, 0, 0x1c000
	s_add_i32 s25, s44, s30
	v_add_u32_e32 v206, s24, v143
	s_add_u32 s44, s22, 0x80
	s_addc_u32 s45, s23, 0
	s_mov_b32 m0, s25
	ds_read_b128 v[194:197], v206
	ds_read_b128 v[198:201], v206 offset:1024
	ds_read_b128 v[202:205], v206 offset:2048
	ds_read_b128 v[206:209], v206 offset:3072
	global_load_lds_dwordx4 v0, s[44:45]
	s_add_i32 m0, s25, 0x2000
	s_nop 0
	global_load_lds_dwordx4 v130, s[44:45]
	s_barrier
	s_waitcnt lgkmcnt(0)
	v_mfma_f32_16x16x32_bf16 v[118:121], v[194:197], v[162:165], v[118:121]
	v_mfma_f32_16x16x32_bf16 v[114:117], v[202:205], v[162:165], v[114:117]
	v_mfma_f32_16x16x32_bf16 v[102:105], v[194:197], v[170:173], v[102:105]
	v_mfma_f32_16x16x32_bf16 v[98:101], v[202:205], v[170:173], v[98:101]
	v_mfma_f32_16x16x32_bf16 v[86:89], v[194:197], v[178:181], v[86:89]
	v_mfma_f32_16x16x32_bf16 v[82:85], v[202:205], v[178:181], v[82:85]
	v_mfma_f32_16x16x32_bf16 v[70:73], v[194:197], v[186:189], v[70:73]
	v_mfma_f32_16x16x32_bf16 v[66:69], v[202:205], v[186:189], v[66:69]
	v_mfma_f32_16x16x32_bf16 v[118:121], v[198:201], v[166:169], v[118:121]
	v_mfma_f32_16x16x32_bf16 v[114:117], v[206:209], v[166:169], v[114:117]
	v_mfma_f32_16x16x32_bf16 v[102:105], v[198:201], v[174:177], v[102:105]
	v_mfma_f32_16x16x32_bf16 v[98:101], v[206:209], v[174:177], v[98:101]
	v_mfma_f32_16x16x32_bf16 v[86:89], v[198:201], v[182:185], v[86:89]
	v_mfma_f32_16x16x32_bf16 v[82:85], v[206:209], v[182:185], v[82:85]
	v_mfma_f32_16x16x32_bf16 v[70:73], v[198:201], v[190:193], v[70:73]
	v_mfma_f32_16x16x32_bf16 v[66:69], v[206:209], v[190:193], v[66:69]
	s_mov_b32 m0, s37
	s_barrier
	ds_read_b128 v[162:165], v145 offset:49152
	ds_read_b128 v[166:169], v145 offset:50176
	ds_read_b128 v[170:173], v145 offset:51200
	ds_read_b128 v[174:177], v145 offset:52224
	ds_read_b128 v[178:181], v145 offset:53248
	ds_read_b128 v[182:185], v145 offset:54272
	ds_read_b128 v[186:189], v145 offset:55296
	ds_read_b128 v[190:193], v145 offset:56320
	global_load_lds_dwordx4 v134, s[48:49]
	s_mov_b32 m0, s38
	s_nop 0
	global_load_lds_dwordx4 v132, s[48:49]
	s_barrier
; __device__ __forceinline__ unsigned cvt_pk_bf16(float lo, float hi) { f32x2_t v = {lo, hi}; bf16x2_t b = __builtin_convertvector(v, bf16x2_t); return __builtin_bit_cast(unsigned, b); }
; #define PG8_STAGE(bufoff, gbase, voff) do { _Pragma("unroll") for (int _i = 0; _i < 2; ++_i) \
;         __builtin_amdgcn_global_load_lds((const unsigned*)((const char*)(gbase) + (voff)[_i]), (LAS unsigned*)(lds + (bufoff) + ldsw + _i * 8192), 16, 0, 0); } while (0)
; #define PG8_LDA(dst, b, h) do { _Pragma("unroll") for (int m = 0; m < 4; ++m) _Pragma("unroll") for (int k = 0; k < 2; ++k) dst[m][k] = *(const LAS bf16x8*)(lds + PG8_SA(b, h) + aoff + m * 2048 + k * 1024); } while (0)
; #define PG8_WAIT_V(n) asm volatile("s_waitcnt vmcnt(" #n ")" ::: "memory")
; template <class Epi, class Sched>
; __device__ __forceinline__ void gemm_phase(LAS unsigned char* lds, const Gemm g, const Sched& S, const Epi& E) {
;     ...
;             PG8_LDA(At, 1, 1); PG8_STAGE(PG8_SA(1, 0), a3, voffA);
;             PG8_BAR; PG8_WAIT_L(0); PG8_MMA(1, 0, At, B0); PG8_BAR; PG8_SCHED;
;             PG8_STAGE(PG8_SB(1, 1), b3 + hstep, voffB);
;             PG8_WAIT_V(6); PG8_BAR; PG8_MMA(1, 1, At, B1); PG8_BAR;
;     __device__ __forceinline__ void operator()(const f32x4 (&acc)[2][2][4][2], const pg8::Unit& u, int wr, int wc, int fr, int fq) const {
;         const int row0 = u.pm * 256 + wr * 64 + fr; const int col0 = u.pn * 256 + wc * 32 + 8 * fq;
; #pragma unroll
;         for (int ai = 0; ai < 2; ++ai)
; #pragma unroll
;             for (int m = 0; m < 4; ++m) { const int row = row0 + ai * 128 + m * 16; bf16_t* rowp = O + (size_t)row * ldc + col0;
; #pragma unroll
;                 for (int bj = 0; bj < 2; ++bj) { f32x4 v0 = acc[ai][bj][m][0], v1 = acc[ai][bj][m][1];
;                     if (ACT == 1) {
; #pragma unroll
;                         for (int j = 0; j < 4; ++j) { float a = fmaxf(v0[j], 0.f), b = fmaxf(v1[j], 0.f); v0[j] = a * a; v1[j] = b * b; } }
;                     if (ACT == 0) { if (u.pn == (C_G / 256) && bj == 0 && wc == 0 && fq < 2) { float* gp = gate + (size_t)row * 16 + 8 * fq; *(f32x4*)gp = v0; *(f32x4*)(gp + 4) = v1; } }
;                     u32x4 w; w.x = cvt_pk_bf16(v0[0], v0[1]); w.y = cvt_pk_bf16(v0[2], v0[3]); w.z = cvt_pk_bf16(v1[0], v1[1]); w.w = cvt_pk_bf16(v1[2], v1[3]);
;                     *(u32x4*)(rowp + bj * 128) = w; } }
	s_waitcnt lgkmcnt(0)
	v_mfma_f32_16x16x32_bf16 v[62:65], v[146:149], v[162:165], v[62:65]
	v_mfma_f32_16x16x32_bf16 v[58:61], v[154:157], v[162:165], v[58:61]
	v_mfma_f32_16x16x32_bf16 v[46:49], v[146:149], v[170:173], v[46:49]
	v_mfma_f32_16x16x32_bf16 v[42:45], v[154:157], v[170:173], v[42:45]
	v_mfma_f32_16x16x32_bf16 v[30:33], v[146:149], v[178:181], v[30:33]
	v_mfma_f32_16x16x32_bf16 v[26:29], v[154:157], v[178:181], v[26:29]
	v_mfma_f32_16x16x32_bf16 v[14:17], v[146:149], v[186:189], v[14:17]
	v_mfma_f32_16x16x32_bf16 v[10:13], v[154:157], v[186:189], v[10:13]
	v_mfma_f32_16x16x32_bf16 v[62:65], v[150:153], v[166:169], v[62:65]
	v_mfma_f32_16x16x32_bf16 v[58:61], v[158:161], v[166:169], v[58:61]
	v_mfma_f32_16x16x32_bf16 v[46:49], v[150:153], v[174:177], v[46:49]
	v_mfma_f32_16x16x32_bf16 v[42:45], v[158:161], v[174:177], v[42:45]
	v_mfma_f32_16x16x32_bf16 v[30:33], v[150:153], v[182:185], v[30:33]
	v_mfma_f32_16x16x32_bf16 v[26:29], v[158:161], v[182:185], v[26:29]
	v_mfma_f32_16x16x32_bf16 v[14:17], v[150:153], v[190:193], v[14:17]
	v_mfma_f32_16x16x32_bf16 v[10:13], v[158:161], v[190:193], v[10:13]
	s_barrier
	s_add_u32 s22, s22, 0x80080
	s_addc_u32 s23, s23, 0
	s_add_i32 s24, s24, s30
	s_mov_b32 m0, s24
	s_nop 0
	global_load_lds_dwordx4 v0, s[22:23]
	s_add_i32 m0, s24, 0x2000
	s_nop 0
	global_load_lds_dwordx4 v130, s[22:23]
	s_waitcnt vmcnt(6)
	s_barrier
	v_mfma_f32_16x16x32_bf16 v[54:57], v[194:197], v[162:165], v[54:57]
	v_mfma_f32_16x16x32_bf16 v[50:53], v[202:205], v[162:165], v[50:53]
	v_mfma_f32_16x16x32_bf16 v[38:41], v[194:197], v[170:173], v[38:41]
	v_mfma_f32_16x16x32_bf16 v[34:37], v[202:205], v[170:173], v[34:37]
	v_mfma_f32_16x16x32_bf16 v[22:25], v[194:197], v[178:181], v[22:25]
	v_mfma_f32_16x16x32_bf16 v[18:21], v[202:205], v[178:181], v[18:21]
	v_mfma_f32_16x16x32_bf16 v[6:9], v[194:197], v[186:189], v[6:9]
	v_mfma_f32_16x16x32_bf16 v[2:5], v[202:205], v[186:189], v[2:5]
	v_mfma_f32_16x16x32_bf16 v[54:57], v[198:201], v[166:169], v[54:57]
	v_mfma_f32_16x16x32_bf16 v[50:53], v[206:209], v[166:169], v[50:53]
	v_mfma_f32_16x16x32_bf16 v[38:41], v[198:201], v[174:177], v[38:41]
	v_mfma_f32_16x16x32_bf16 v[34:37], v[206:209], v[174:177], v[34:37]
	v_mfma_f32_16x16x32_bf16 v[22:25], v[198:201], v[182:185], v[22:25]
	v_mfma_f32_16x16x32_bf16 v[18:21], v[206:209], v[182:185], v[18:21]
	v_mfma_f32_16x16x32_bf16 v[6:9], v[198:201], v[190:193], v[6:9]
	v_mfma_f32_16x16x32_bf16 v[2:5], v[206:209], v[190:193], v[2:5]
	s_add_i32 s43, s43, 2
	s_add_u32 s20, s20, 0x100
	s_addc_u32 s21, s21, 0
	s_add_u32 s41, s41, 0x100
	s_addc_u32 s42, s42, 0
	s_cmp_gt_u32 s43, 29
	s_barrier
	s_cbranch_scc0 .LBB0_1279
	v_lshl_add_u32 v146, s18, 8, v142
	v_lshl_or_b32 v140, s16, 8, v144
	v_ashrrev_i32_e32 v147, 31, v146
	v_ashrrev_i32_e32 v141, 31, v140
	v_lshlrev_b64 v[148:149], 14, v[146:147]
	v_lshl_add_u64 v[148:149], s[58:59], 0, v[148:149]
	v_lshlrev_b64 v[150:151], 1, v[140:141]
	v_max_f32_e32 v122, 0, v122
	v_max_f32_e32 v123, 0, v123
	v_lshl_add_u64 v[140:141], v[148:149], 0, v[150:151]
	v_pk_mul_f32 v[148:149], v[122:123], v[122:123]
	v_max_f32_e32 v124, 0, v124
	v_max_f32_e32 v126, 0, v126
	v_max_f32_e32 v127, 0, v127
	v_max_f32_e32 v122, 0, v128
	v_max_f32_e32 v123, 0, v129
	v_max_f32_e32 v125, 0, v125
	v_pk_mul_f32 v[126:127], v[126:127], v[126:127]
	v_pk_mul_f32 v[128:129], v[122:123], v[122:123]
	v_pk_mul_f32 v[152:153], v[124:125], v[124:125]
	v_cvt_pk_bf16_f32 v122, v126, v127
	v_cvt_pk_bf16_f32 v123, v128, v129
	v_cvt_pk_bf16_f32 v124, v148, v149
	v_cvt_pk_bf16_f32 v125, v152, v153
	v_max_f32_e32 v114, 0, v114
	v_max_f32_e32 v115, 0, v115
	global_store_dwordx4 v[140:141], v[122:125], off
	s_nop 1
	v_pk_mul_f32 v[122:123], v[114:115], v[114:115]
	v_max_f32_e32 v116, 0, v116
	v_max_f32_e32 v118, 0, v118
	v_max_f32_e32 v119, 0, v119
	v_max_f32_e32 v114, 0, v120
	v_max_f32_e32 v115, 0, v121
	v_max_f32_e32 v117, 0, v117
	v_pk_mul_f32 v[118:119], v[118:119], v[118:119]
	v_pk_mul_f32 v[120:121], v[114:115], v[114:115]
	v_pk_mul_f32 v[124:125], v[116:117], v[116:117]
	v_cvt_pk_bf16_f32 v114, v118, v119
	v_cvt_pk_bf16_f32 v115, v120, v121
	v_cvt_pk_bf16_f32 v116, v122, v123
	v_cvt_pk_bf16_f32 v117, v124, v125
	v_max_f32_e32 v106, 0, v106
	v_max_f32_e32 v107, 0, v107
	global_store_dwordx4 v[140:141], v[114:117], off offset:256
	s_nop 1
	v_or_b32_e32 v114, 16, v146
	v_pk_mul_f32 v[116:117], v[106:107], v[106:107]
	v_ashrrev_i32_e32 v115, 31, v114
	v_max_f32_e32 v108, 0, v108
	v_lshlrev_b64 v[114:115], 14, v[114:115]
	v_max_f32_e32 v110, 0, v110
	v_max_f32_e32 v111, 0, v111
	v_max_f32_e32 v106, 0, v112
	v_max_f32_e32 v107, 0, v113
	v_max_f32_e32 v109, 0, v109
	v_lshl_add_u64 v[114:115], s[58:59], 0, v[114:115]
	v_pk_mul_f32 v[110:111], v[110:111], v[110:111]
	v_pk_mul_f32 v[112:113], v[106:107], v[106:107]
	v_pk_mul_f32 v[118:119], v[108:109], v[108:109]
	v_lshl_add_u64 v[114:115], v[114:115], 0, v[150:151]
	v_cvt_pk_bf16_f32 v106, v110, v111
	v_cvt_pk_bf16_f32 v107, v112, v113
	v_cvt_pk_bf16_f32 v108, v116, v117
	v_cvt_pk_bf16_f32 v109, v118, v119
	v_max_f32_e32 v98, 0, v98
	v_max_f32_e32 v99, 0, v99
	global_store_dwordx4 v[114:115], v[106:109], off
	s_nop 1
	v_pk_mul_f32 v[106:107], v[98:99], v[98:99]
	v_max_f32_e32 v100, 0, v100
	v_max_f32_e32 v102, 0, v102
	v_max_f32_e32 v103, 0, v103
	v_max_f32_e32 v98, 0, v104
	v_max_f32_e32 v99, 0, v105
	v_max_f32_e32 v101, 0, v101
	v_pk_mul_f32 v[102:103], v[102:103], v[102:103]
	v_pk_mul_f32 v[104:105], v[98:99], v[98:99]
	v_pk_mul_f32 v[108:109], v[100:101], v[100:101]
	v_cvt_pk_bf16_f32 v98, v102, v103
	v_cvt_pk_bf16_f32 v99, v104, v105
	v_cvt_pk_bf16_f32 v100, v106, v107
; __device__ __forceinline__ unsigned cvt_pk_bf16(float lo, float hi) { f32x2_t v = {lo, hi}; bf16x2_t b = __builtin_convertvector(v, bf16x2_t); return __builtin_bit_cast(unsigned, b); }
;     __device__ __forceinline__ void operator()(const f32x4 (&acc)[2][2][4][2], const pg8::Unit& u, int wr, int wc, int fr, int fq) const {
;     ...
;             for (int m = 0; m < 4; ++m) { const int row = row0 + ai * 128 + m * 16; bf16_t* rowp = O + (size_t)row * ldc + col0;
; #pragma unroll
;                 for (int bj = 0; bj < 2; ++bj) { f32x4 v0 = acc[ai][bj][m][0], v1 = acc[ai][bj][m][1];
;                     if (ACT == 1) {
; #pragma unroll
;                         for (int j = 0; j < 4; ++j) { float a = fmaxf(v0[j], 0.f), b = fmaxf(v1[j], 0.f); v0[j] = a * a; v1[j] = b * b; } }
;                     if (ACT == 0) { if (u.pn == (C_G / 256) && bj == 0 && wc == 0 && fq < 2) { float* gp = gate + (size_t)row * 16 + 8 * fq; *(f32x4*)gp = v0; *(f32x4*)(gp + 4) = v1; } }
;                     u32x4 w; w.x = cvt_pk_bf16(v0[0], v0[1]); w.y = cvt_pk_bf16(v0[2], v0[3]); w.z = cvt_pk_bf16(v1[0], v1[1]); w.w = cvt_pk_bf16(v1[2], v1[3]);
;                     *(u32x4*)(rowp + bj * 128) = w; } }
	v_cvt_pk_bf16_f32 v101, v108, v109
	v_max_f32_e32 v90, 0, v90
	v_max_f32_e32 v91, 0, v91
	global_store_dwordx4 v[114:115], v[98:101], off offset:256
	s_nop 1
	v_or_b32_e32 v98, 32, v146
	v_pk_mul_f32 v[100:101], v[90:91], v[90:91]
	v_ashrrev_i32_e32 v99, 31, v98
	v_max_f32_e32 v92, 0, v92
	v_lshlrev_b64 v[98:99], 14, v[98:99]
	v_max_f32_e32 v94, 0, v94
	v_max_f32_e32 v95, 0, v95
	v_max_f32_e32 v90, 0, v96
	v_max_f32_e32 v91, 0, v97
	v_max_f32_e32 v93, 0, v93
	v_lshl_add_u64 v[98:99], s[58:59], 0, v[98:99]
	v_pk_mul_f32 v[94:95], v[94:95], v[94:95]
	v_pk_mul_f32 v[96:97], v[90:91], v[90:91]
	v_pk_mul_f32 v[102:103], v[92:93], v[92:93]
	v_lshl_add_u64 v[98:99], v[98:99], 0, v[150:151]
	v_cvt_pk_bf16_f32 v90, v94, v95
	v_cvt_pk_bf16_f32 v91, v96, v97
	v_cvt_pk_bf16_f32 v92, v100, v101
	v_cvt_pk_bf16_f32 v93, v102, v103
	v_max_f32_e32 v82, 0, v82
	v_max_f32_e32 v83, 0, v83
	global_store_dwordx4 v[98:99], v[90:93], off
	s_nop 1
	v_pk_mul_f32 v[90:91], v[82:83], v[82:83]
	v_max_f32_e32 v84, 0, v84
	v_max_f32_e32 v86, 0, v86
	v_max_f32_e32 v87, 0, v87
	v_max_f32_e32 v82, 0, v88
	v_max_f32_e32 v83, 0, v89
	v_max_f32_e32 v85, 0, v85
	v_pk_mul_f32 v[86:87], v[86:87], v[86:87]
	v_pk_mul_f32 v[88:89], v[82:83], v[82:83]
	v_pk_mul_f32 v[92:93], v[84:85], v[84:85]
	v_cvt_pk_bf16_f32 v82, v86, v87
	v_cvt_pk_bf16_f32 v83, v88, v89
	v_cvt_pk_bf16_f32 v84, v90, v91
	v_cvt_pk_bf16_f32 v85, v92, v93
	v_max_f32_e32 v74, 0, v74
	v_max_f32_e32 v75, 0, v75
	global_store_dwordx4 v[98:99], v[82:85], off offset:256
	s_nop 1
	v_or_b32_e32 v82, 48, v146
	v_pk_mul_f32 v[84:85], v[74:75], v[74:75]
	v_ashrrev_i32_e32 v83, 31, v82
	v_max_f32_e32 v76, 0, v76
	v_lshlrev_b64 v[82:83], 14, v[82:83]
	v_max_f32_e32 v78, 0, v78
	v_max_f32_e32 v79, 0, v79
	v_max_f32_e32 v74, 0, v80
	v_max_f32_e32 v75, 0, v81
	v_max_f32_e32 v77, 0, v77
	v_lshl_add_u64 v[82:83], s[58:59], 0, v[82:83]
	v_pk_mul_f32 v[78:79], v[78:79], v[78:79]
	v_pk_mul_f32 v[80:81], v[74:75], v[74:75]
	v_pk_mul_f32 v[86:87], v[76:77], v[76:77]
	v_lshl_add_u64 v[82:83], v[82:83], 0, v[150:151]
	v_cvt_pk_bf16_f32 v74, v78, v79
	v_cvt_pk_bf16_f32 v75, v80, v81
	v_cvt_pk_bf16_f32 v76, v84, v85
	v_cvt_pk_bf16_f32 v77, v86, v87
	v_max_f32_e32 v66, 0, v66
	v_max_f32_e32 v67, 0, v67
	global_store_dwordx4 v[82:83], v[74:77], off
	s_nop 1
	v_pk_mul_f32 v[74:75], v[66:67], v[66:67]
	v_max_f32_e32 v68, 0, v68
	v_max_f32_e32 v70, 0, v70
	v_max_f32_e32 v71, 0, v71
	v_max_f32_e32 v66, 0, v72
	v_max_f32_e32 v67, 0, v73
	v_max_f32_e32 v69, 0, v69
	v_pk_mul_f32 v[70:71], v[70:71], v[70:71]
	v_pk_mul_f32 v[72:73], v[66:67], v[66:67]
	v_pk_mul_f32 v[76:77], v[68:69], v[68:69]
	v_cvt_pk_bf16_f32 v66, v70, v71
	v_cvt_pk_bf16_f32 v67, v72, v73
	v_cvt_pk_bf16_f32 v68, v74, v75
	v_cvt_pk_bf16_f32 v69, v76, v77
	v_max_f32_e32 v58, 0, v58
	v_max_f32_e32 v59, 0, v59
	global_store_dwordx4 v[82:83], v[66:69], off offset:256
	s_nop 1
	v_pk_mul_f32 v[68:69], v[58:59], v[58:59]
	v_max_f32_e32 v62, 0, v62
	v_max_f32_e32 v63, 0, v63
	v_max_f32_e32 v60, 0, v60
	v_pk_mul_f32 v[62:63], v[62:63], v[62:63]
	v_max_f32_e32 v58, 0, v64
	v_max_f32_e32 v59, 0, v65
	v_max_f32_e32 v61, 0, v61
	s_mov_b32 s3, 0x200000
	v_pk_mul_f32 v[64:65], v[58:59], v[58:59]
	v_pk_mul_f32 v[70:71], v[60:61], v[60:61]
	v_cvt_pk_bf16_f32 v58, v62, v63
	v_add_co_u32_e32 v62, vcc, s3, v140
	v_cvt_pk_bf16_f32 v59, v64, v65
	v_cvt_pk_bf16_f32 v60, v68, v69
	v_cvt_pk_bf16_f32 v61, v70, v71
	v_addc_co_u32_e32 v63, vcc, 0, v141, vcc
	v_max_f32_e32 v50, 0, v50
	v_max_f32_e32 v51, 0, v51
	global_store_dwordx4 v[62:63], v[58:61], off
	s_nop 1
	v_pk_mul_f32 v[58:59], v[50:51], v[50:51]
	v_max_f32_e32 v52, 0, v52
	v_max_f32_e32 v54, 0, v54
	v_max_f32_e32 v55, 0, v55
	v_max_f32_e32 v50, 0, v56
	v_max_f32_e32 v51, 0, v57
	v_max_f32_e32 v53, 0, v53
	s_mov_b64 s[20:21], 0x200000
	v_pk_mul_f32 v[54:55], v[54:55], v[54:55]
	v_pk_mul_f32 v[56:57], v[50:51], v[50:51]
	v_pk_mul_f32 v[60:61], v[52:53], v[52:53]
	v_lshl_add_u64 v[66:67], v[140:141], 0, s[20:21]
	v_cvt_pk_bf16_f32 v50, v54, v55
	v_cvt_pk_bf16_f32 v51, v56, v57
	v_cvt_pk_bf16_f32 v52, v58, v59
	v_cvt_pk_bf16_f32 v53, v60, v61
	v_max_f32_e32 v42, 0, v42
	v_max_f32_e32 v43, 0, v43
	global_store_dwordx4 v[66:67], v[50:53], off offset:256
; __device__ __forceinline__ unsigned cvt_pk_bf16(float lo, float hi) { f32x2_t v = {lo, hi}; bf16x2_t b = __builtin_convertvector(v, bf16x2_t); return __builtin_bit_cast(unsigned, b); }
; #define PG8_WAIT_V(n) asm volatile("s_waitcnt vmcnt(" #n ")" ::: "memory")
; #define PG8_BAR __builtin_amdgcn_s_barrier()
; template <class Epi, class Sched>
; __device__ __forceinline__ void gemm_phase(LAS unsigned char* lds, const Gemm g, const Sched& S, const Epi& E) {
;     ...
;         if (!has_next) break;
; #pragma unroll
;         for (int a = 0; a < 2; ++a)
; #pragma unroll
;             for (int b = 0; b < 2; ++b)
; #pragma unroll
;                 for (int m = 0; m < 4; ++m)
; #pragma unroll
;                     for (int n = 0; n < 2; ++n) acc[a][b][m][n] = (f32x4){0.f, 0.f, 0.f, 0.f};
;         cur = nxt; cA = nA; cB = nB; ++ui;
;     }
;     PG8_WAIT_V(0);
;     if (wr == 0) PG8_BAR;
;     PG8_BAR;
;     __device__ __forceinline__ void operator()(const f32x4 (&acc)[2][2][4][2], const pg8::Unit& u, int wr, int wc, int fr, int fq) const {
;     ...
;             for (int m = 0; m < 4; ++m) { const int row = row0 + ai * 128 + m * 16; bf16_t* rowp = O + (size_t)row * ldc + col0;
; #pragma unroll
;                 for (int bj = 0; bj < 2; ++bj) { f32x4 v0 = acc[ai][bj][m][0], v1 = acc[ai][bj][m][1];
;                     if (ACT == 1) {
; #pragma unroll
;                         for (int j = 0; j < 4; ++j) { float a = fmaxf(v0[j], 0.f), b = fmaxf(v1[j], 0.f); v0[j] = a * a; v1[j] = b * b; } }
;                     if (ACT == 0) { if (u.pn == (C_G / 256) && bj == 0 && wc == 0 && fq < 2) { float* gp = gate + (size_t)row * 16 + 8 * fq; *(f32x4*)gp = v0; *(f32x4*)(gp + 4) = v1; } }
;                     u32x4 w; w.x = cvt_pk_bf16(v0[0], v0[1]); w.y = cvt_pk_bf16(v0[2], v0[3]); w.z = cvt_pk_bf16(v1[0], v1[1]); w.w = cvt_pk_bf16(v1[2], v1[3]);
;                     *(u32x4*)(rowp + bj * 128) = w; } }
	s_nop 1
	v_pk_mul_f32 v[52:53], v[42:43], v[42:43]
	v_max_f32_e32 v46, 0, v46
	v_max_f32_e32 v47, 0, v47
	v_max_f32_e32 v44, 0, v44
	v_pk_mul_f32 v[46:47], v[46:47], v[46:47]
	v_max_f32_e32 v42, 0, v48
	v_max_f32_e32 v43, 0, v49
	v_max_f32_e32 v45, 0, v45
	s_mov_b32 s3, 0x240000
	v_pk_mul_f32 v[48:49], v[42:43], v[42:43]
	v_pk_mul_f32 v[54:55], v[44:45], v[44:45]
	v_cvt_pk_bf16_f32 v42, v46, v47
	v_add_co_u32_e32 v46, vcc, s3, v140
	v_cvt_pk_bf16_f32 v43, v48, v49
	v_cvt_pk_bf16_f32 v44, v52, v53
	v_cvt_pk_bf16_f32 v45, v54, v55
	v_addc_co_u32_e32 v47, vcc, 0, v141, vcc
	v_max_f32_e32 v34, 0, v34
	v_max_f32_e32 v35, 0, v35
	global_store_dwordx4 v[46:47], v[42:45], off
	s_nop 1
	v_pk_mul_f32 v[42:43], v[34:35], v[34:35]
	v_max_f32_e32 v36, 0, v36
	v_max_f32_e32 v38, 0, v38
	v_max_f32_e32 v39, 0, v39
	v_max_f32_e32 v34, 0, v40
	v_max_f32_e32 v35, 0, v41
	v_max_f32_e32 v37, 0, v37
	s_mov_b64 s[20:21], 0x240000
	v_pk_mul_f32 v[38:39], v[38:39], v[38:39]
	v_pk_mul_f32 v[40:41], v[34:35], v[34:35]
	v_pk_mul_f32 v[44:45], v[36:37], v[36:37]
	v_lshl_add_u64 v[50:51], v[140:141], 0, s[20:21]
	v_cvt_pk_bf16_f32 v34, v38, v39
	v_cvt_pk_bf16_f32 v35, v40, v41
	v_cvt_pk_bf16_f32 v36, v42, v43
	v_cvt_pk_bf16_f32 v37, v44, v45
	v_max_f32_e32 v26, 0, v26
	v_max_f32_e32 v27, 0, v27
	global_store_dwordx4 v[50:51], v[34:37], off offset:256
	s_nop 1
	v_pk_mul_f32 v[36:37], v[26:27], v[26:27]
	v_max_f32_e32 v30, 0, v30
	v_max_f32_e32 v31, 0, v31
	v_max_f32_e32 v28, 0, v28
	v_pk_mul_f32 v[30:31], v[30:31], v[30:31]
	v_max_f32_e32 v26, 0, v32
	v_max_f32_e32 v27, 0, v33
	v_max_f32_e32 v29, 0, v29
	s_mov_b32 s3, 0x280000
	v_pk_mul_f32 v[32:33], v[26:27], v[26:27]
	v_pk_mul_f32 v[38:39], v[28:29], v[28:29]
	v_cvt_pk_bf16_f32 v26, v30, v31
	v_add_co_u32_e32 v30, vcc, s3, v140
	v_cvt_pk_bf16_f32 v27, v32, v33
	v_cvt_pk_bf16_f32 v28, v36, v37
	v_cvt_pk_bf16_f32 v29, v38, v39
	v_addc_co_u32_e32 v31, vcc, 0, v141, vcc
	v_max_f32_e32 v18, 0, v18
	v_max_f32_e32 v19, 0, v19
	global_store_dwordx4 v[30:31], v[26:29], off
	s_nop 1
	v_pk_mul_f32 v[26:27], v[18:19], v[18:19]
	v_max_f32_e32 v20, 0, v20
	v_max_f32_e32 v22, 0, v22
	v_max_f32_e32 v23, 0, v23
	v_max_f32_e32 v18, 0, v24
	v_max_f32_e32 v19, 0, v25
	v_max_f32_e32 v21, 0, v21
	s_mov_b64 s[20:21], 0x280000
	v_pk_mul_f32 v[22:23], v[22:23], v[22:23]
	v_pk_mul_f32 v[24:25], v[18:19], v[18:19]
	v_pk_mul_f32 v[28:29], v[20:21], v[20:21]
	v_lshl_add_u64 v[34:35], v[140:141], 0, s[20:21]
	v_cvt_pk_bf16_f32 v18, v22, v23
	v_cvt_pk_bf16_f32 v19, v24, v25
	v_cvt_pk_bf16_f32 v20, v26, v27
	v_cvt_pk_bf16_f32 v21, v28, v29
	v_max_f32_e32 v10, 0, v10
	v_max_f32_e32 v11, 0, v11
	global_store_dwordx4 v[34:35], v[18:21], off offset:256
	s_nop 1
	v_pk_mul_f32 v[20:21], v[10:11], v[10:11]
	v_max_f32_e32 v14, 0, v14
	v_max_f32_e32 v15, 0, v15
	v_max_f32_e32 v12, 0, v12
	v_pk_mul_f32 v[14:15], v[14:15], v[14:15]
	v_max_f32_e32 v10, 0, v16
	v_max_f32_e32 v11, 0, v17
	v_max_f32_e32 v13, 0, v13
	s_mov_b32 s3, 0x2c0000
	v_pk_mul_f32 v[16:17], v[10:11], v[10:11]
	v_pk_mul_f32 v[22:23], v[12:13], v[12:13]
	v_cvt_pk_bf16_f32 v10, v14, v15
	v_add_co_u32_e32 v14, vcc, s3, v140
	v_cvt_pk_bf16_f32 v11, v16, v17
	v_cvt_pk_bf16_f32 v12, v20, v21
	v_cvt_pk_bf16_f32 v13, v22, v23
	v_addc_co_u32_e32 v15, vcc, 0, v141, vcc
	v_max_f32_e32 v2, 0, v2
	v_max_f32_e32 v3, 0, v3
	global_store_dwordx4 v[14:15], v[10:13], off
	s_nop 1
	v_pk_mul_f32 v[10:11], v[2:3], v[2:3]
	v_max_f32_e32 v4, 0, v4
	v_max_f32_e32 v6, 0, v6
	v_max_f32_e32 v7, 0, v7
	v_max_f32_e32 v2, 0, v8
	v_max_f32_e32 v3, 0, v9
	v_max_f32_e32 v5, 0, v5
	s_mov_b64 s[20:21], 0x2c0000
	v_pk_mul_f32 v[6:7], v[6:7], v[6:7]
	v_pk_mul_f32 v[8:9], v[2:3], v[2:3]
	v_pk_mul_f32 v[12:13], v[4:5], v[4:5]
	v_lshl_add_u64 v[18:19], v[140:141], 0, s[20:21]
	v_cvt_pk_bf16_f32 v2, v6, v7
	v_cvt_pk_bf16_f32 v3, v8, v9
	v_cvt_pk_bf16_f32 v4, v10, v11
	v_cvt_pk_bf16_f32 v5, v12, v13
	s_and_b64 vcc, exec, s[0:1]
	s_mov_b32 s16, s8
	s_mov_b32 s18, s10
	s_mov_b64 s[22:23], s[14:15]
	s_mov_b64 s[20:21], s[12:13]
	global_store_dwordx4 v[18:19], v[2:5], off offset:256
	s_nop 1
	s_cbranch_vccz .LBB0_1276
	s_waitcnt vmcnt(0)
	s_cmpk_gt_u32 s27, 0xff
	s_cbranch_scc1 .LBB0_1283
	s_barrier
